# as previous with 40 (instead of 16) softmax VALU ops issued ahead of the first QK MFMA
# speedup vs baseline: 1.0122x; 1.0022x over previous
; __device__ __forceinline__ void finishSM(f32x16& p0, f32x16& p1, float alpha, float& l_reg, bf16x8& pa0, bf16x8& pa1, bf16x8& pa2, bf16x8& pa3) {
;   for (int r = 0; r < 16; ++r) p1[r] = __builtin_amdgcn_exp2f(p1[r]);
;   float ps = 0; for (int r = 0; r < 16; ++r) ps += p0[r]; for (int r = 0; r < 16; ++r) ps += p1[r];
;   { auto rr = __builtin_amdgcn_permlane32_swap(__float_as_uint(ps), __float_as_uint(ps), false, false);
;     ps = __uint_as_float(rr[0]) + __uint_as_float(rr[1]); }
;   l_reg = l_reg * alpha + ps;
;     ...
;   PK4(p0, 0, pa0); PK4(p0, 8, pa1); PK4(p1, 0, pa2); PK4(p1, 8, pa3);
;     ...
; }
; __device__ __forceinline__ void kload(bf16x8 (&kf)[8], const char* Ks, int r32, int hi, int sb) {
; #pragma unroll
;   for (int d0 = 0; d0 < 4; ++d0) { const int cb = sb + (d0 * 16 + hi * 8) * 2;
;     kf[2 * d0] = *reinterpret_cast<const bf16x8*>(Ks + KSWZ(r32, cb)); kf[2 * d0 + 1] = *reinterpret_cast<const bf16x8*>(Ks + KSWZ(32 + r32, cb)); }
; }
; __device__ __forceinline__ void kmma(f32x16& p0, f32x16& p1, const bf16x8 (&kf)[8], const bf16x8* qr) {
;   asm volatile("s_waitcnt lgkmcnt(0)" ::: "memory"); SBAR();
;   p0 = f32x16{}; p1 = f32x16{};
; #pragma unroll
;   for (int d0 = 0; d0 < 4; ++d0) { p0 = __builtin_amdgcn_mfma_f32_32x32x16_bf16(kf[2 * d0], qr[d0], p0, 0, 0, 0); p1 = __builtin_amdgcn_mfma_f32_32x32x16_bf16(kf[2 * d0 + 1], qr[d0], p1, 0, 0, 0); }
; }
; __device__ __forceinline__ void qkt(f32x16& p0, f32x16& p1, const char* Ks, const bf16x8* qr, int r32, int hi, int sb) {
;   bf16x8 kf[8]; kload(kf, Ks, r32, hi, sb); SBAR(); kmma(p0, p1, kf, qr);
; }
; __device__ __forceinline__ int v_st(int k, int c) { const int kk = (k & ~0xC) | ((k & 4) << 1) | ((k & 8) >> 1); return ((kk >> 3) * 4 + (c >> 5)) * 512 + ((kk & 7) * 32 + (c & 31)) * 2; }
; __device__ __forceinline__ int v_rd_base(int lane) { return ((lane & 3) << 3) | (((lane >> 2) & 3) << 6) | (((lane >> 4) & 1) << 5) | (((lane >> 5) & 1) << 8); }
; template <int OFF> __device__ __forceinline__ s16x4 tr_read(int vb) {
;   s16x4 r; asm volatile("ds_read_b64_tr_b16 %0, %1 offset:%2" : "=&v"(r) : "v"(vb), "i"(OFF) : "memory"); return r;
; }
; template <int D0> __device__ __forceinline__ void v_frag_read(VFrag& f, int vb) {
;   f.l0 = tr_read<v_rd_off(D0, 0, 0)>(vb); f.h0 = tr_read<v_rd_off(D0, 0, 1)>(vb); f.l1 = tr_read<v_rd_off(D0, 1, 0)>(vb); f.h1 = tr_read<v_rd_off(D0, 1, 1)>(vb);
.LBB0_770:
	ds_read_b128 v[82:85], v245
	ds_read_b128 v[86:89], v245 offset:8192
	ds_read_b128 v[130:133], v246
	ds_read_b128 v[134:137], v246 offset:8192
	ds_read_b128 v[206:209], v247
	ds_read_b128 v[210:213], v247 offset:8192
	ds_read_b128 v[214:217], v255
	ds_read_b128 v[218:221], v255 offset:8192
	s_and_b32 s13, s36, 0xc000
	v_add_u32_e32 v244, s13, v164
	ds_read_b64_tr_b16 v[228:229], v244 offset:0
	ds_read_b64_tr_b16 v[230:231], v244 offset:0x800
	ds_read_b64_tr_b16 v[232:233], v244 offset:0x1000
	ds_read_b64_tr_b16 v[234:235], v244 offset:0x1800
	ds_read_b64_tr_b16 v[236:237], v244 offset:0x2000
	ds_read_b64_tr_b16 v[238:239], v244 offset:0x2800
	ds_read_b64_tr_b16 v[240:241], v244 offset:0x3000
	ds_read_b64_tr_b16 v[242:243], v244 offset:0x3800
	v_exp_f32_e32 v148, v66
	v_add_f32_e32 v66, 0, v175
	v_add_f32_e32 v66, v177, v66
	v_add_f32_e32 v66, v192, v66
	v_add_f32_e32 v66, v195, v66
	v_add_f32_e32 v66, v196, v66
	v_add_f32_e32 v66, v199, v66
	v_add_f32_e32 v66, v200, v66
	v_add_f32_e32 v66, v203, v66
	v_add_f32_e32 v66, v176, v66
	v_add_f32_e32 v66, v193, v66
	v_add_f32_e32 v66, v194, v66
	v_add_f32_e32 v66, v197, v66
	v_add_f32_e32 v66, v198, v66
	v_exp_f32_e32 v149, v67
	v_add_f32_e32 v66, v201, v66
	v_exp_f32_e32 v150, v68
	v_add_f32_e32 v66, v202, v66
	v_exp_f32_e32 v151, v69
	v_add_f32_e32 v66, v204, v66
	v_exp_f32_e32 v186, v70
	v_add_f32_e32 v66, v148, v66
	v_exp_f32_e32 v187, v71
	v_add_f32_e32 v66, v149, v66
	v_exp_f32_e32 v188, v72
	v_add_f32_e32 v66, v150, v66
	v_exp_f32_e32 v189, v73
	v_add_f32_e32 v66, v151, v66
	v_exp_f32_e32 v205, v74
	v_add_f32_e32 v66, v186, v66
	v_exp_f32_e32 v222, v75
	v_add_f32_e32 v66, v187, v66
	v_exp_f32_e32 v223, v76
	v_add_f32_e32 v66, v188, v66
	v_exp_f32_e32 v224, v77
	v_add_f32_e32 v66, v189, v66
	v_exp_f32_e32 v225, v78
	v_add_f32_e32 v66, v205, v66
	v_exp_f32_e32 v226, v79
	v_add_f32_e32 v66, v222, v66
	s_waitcnt lgkmcnt(15)
	v_mfma_f32_32x32x16_bf16 v[98:113], v[82:85], v[126:129], 0
	v_exp_f32_e32 v227, v80
	s_add_i32 s37, s12, 2
	s_cmpk_lt_u32 s12, 0x7e
	s_cselect_b64 s[0:1], -1, 0
	s_and_b64 s[10:11], s[0:1], exec
	s_cselect_b32 s10, 0, 0xffffff80
	s_waitcnt lgkmcnt(14)
	v_mfma_f32_32x32x16_bf16 v[82:97], v[86:89], v[126:129], 0
	v_add_f32_e32 v66, v223, v66
	s_add_i32 s58, s37, s10
	v_exp_f32_e32 v81, v81
	s_and_b64 s[0:1], s[0:1], exec
	s_cselect_b32 s1, s9, s30
	s_cselect_b32 s0, s8, s26
	s_lshl_b64 s[10:11], s[58:59], 17
	s_lshl_b64 s[0:1], s[0:1], 11
	s_waitcnt lgkmcnt(13)
	v_mfma_f32_32x32x16_bf16 v[98:113], v[130:133], v[122:125], v[98:113]
	v_add_f32_e32 v66, v224, v66
	s_add_u32 s10, s10, s0
	s_addc_u32 s11, s11, s1
	s_add_u32 s0, s20, s10
	s_addc_u32 s1, s21, s11
	s_add_u32 s10, s22, s10
	s_waitcnt lgkmcnt(12)
	v_mfma_f32_32x32x16_bf16 v[82:97], v[134:137], v[122:125], v[82:97]
	v_add_f32_e32 v66, v225, v66
	s_addc_u32 s11, s23, s11
	v_add_f32_e32 v66, v226, v66
	s_and_b32 s13, s37, 0xff
	s_mulk_i32 s13, 0xab
	s_lshr_b32 s13, s13, 9
	s_mul_i32 s13, s13, 3
	s_sub_i32 s13, s37, s13
	s_waitcnt lgkmcnt(11)
	v_mfma_f32_32x32x16_bf16 v[98:113], v[206:209], v[118:121], v[98:113]
	v_add_f32_e32 v66, v227, v66
	s_and_b32 s13, s13, 0xff
	s_lshl_b32 s13, s13, 14
	s_mov_b32 s100, s13
	s_add_i32 s42, s36, 0xffffc000
	s_and_b32 s42, s42, 0xc000
	s_add_i32 s13, s13, s27
	s_waitcnt lgkmcnt(10)
	v_mfma_f32_32x32x16_bf16 v[82:97], v[210:213], v[118:121], v[82:97]
	v_add_f32_e32 v130, v81, v66
	s_add_i32 s42, s42, s31
	v_mov_b32_e32 v131, v130
	v_lshl_add_u64 v[246:247], s[0:1], 0, v[146:147]
	s_mov_b32 m0, s13
	s_nop 0
	global_load_lds_dwordx4 v[246:247], off
	v_lshl_add_u64 v[246:247], s[10:11], 0, v[142:143]
	s_waitcnt lgkmcnt(9)
	v_mfma_f32_32x32x16_bf16 v[98:113], v[214:217], v[114:117], v[98:113]
	v_cvt_pk_bf16_f32 v66, v175, v177
	s_mov_b32 m0, s42
	s_nop 0
	global_load_lds_dwordx4 v[246:247], off
	v_lshl_add_u64 v[246:247], s[0:1], 0, v[144:145]
	s_add_i32 m0, s13, 0x2000
	s_waitcnt lgkmcnt(8)
	v_mfma_f32_32x32x16_bf16 v[82:97], v[218:221], v[114:117], v[82:97]
	v_cvt_pk_bf16_f32 v67, v192, v195
	s_nop 0
	v_cvt_pk_bf16_f32 v68, v196, v199
	global_load_lds_dwordx4 v[246:247], off
	v_lshl_add_u64 v[246:247], s[10:11], 0, v[154:155]
	s_add_i32 m0, s42, 0x2000
	s_nop 0
	global_load_lds_dwordx4 v[246:247], off
	v_permlane32_swap_b32_e32 v130, v131
	v_cvt_pk_bf16_f32 v69, v200, v203
	v_permlane32_swap_b32_e32 v66, v68
	v_cvt_pk_bf16_f32 v70, v176, v193
	v_cvt_pk_bf16_f32 v71, v194, v197
	v_cvt_pk_bf16_f32 v72, v198, v201
	v_cvt_pk_bf16_f32 v73, v202, v204
	v_cvt_pk_bf16_f32 v74, v148, v149
	v_cvt_pk_bf16_f32 v75, v150, v151
	v_cvt_pk_bf16_f32 v76, v186, v187
	v_cvt_pk_bf16_f32 v77, v188, v189
	v_cvt_pk_bf16_f32 v78, v205, v222
	v_cvt_pk_bf16_f32 v79, v223, v224
	v_cvt_pk_bf16_f32 v80, v225, v226
	v_cvt_pk_bf16_f32 v81, v227, v81
	v_permlane32_swap_b32_e32 v67, v69
	v_permlane32_swap_b32_e32 v70, v72
	v_permlane32_swap_b32_e32 v71, v73
	v_permlane32_swap_b32_e32 v74, v76
	v_permlane32_swap_b32_e32 v75, v77
	v_permlane32_swap_b32_e32 v78, v80
	v_permlane32_swap_b32_e32 v79, v81
	ds_read_b64_tr_b16 v[204:205], v244 offset:0x200
	ds_read_b64_tr_b16 v[206:207], v244 offset:0xa00
	ds_read_b64_tr_b16 v[208:209], v244 offset:0x1200
	ds_read_b64_tr_b16 v[210:211], v244 offset:0x1a00
	ds_read_b64_tr_b16 v[212:213], v244 offset:0x2200
	ds_read_b64_tr_b16 v[214:215], v244 offset:0x2a00
	ds_read_b64_tr_b16 v[216:217], v244 offset:0x3200
	ds_read_b64_tr_b16 v[218:219], v244 offset:0x3a00
	s_waitcnt lgkmcnt(14)
	v_mfma_f32_32x32x16_bf16 v[18:33], v[66:69], v[228:231], v[18:33]
	v_max_f32_e32 v245, v99, v99
	v_max_f32_e32 v246, v98, v98
	v_max_f32_e32 v245, v246, v245
	v_max3_f32 v245, v245, v100, v101
	v_max3_f32 v245, v245, v102, v103
	v_max3_f32 v245, v245, v104, v105
	v_max3_f32 v245, v245, v106, v107
	v_max3_f32 v245, v245, v108, v109
	s_waitcnt lgkmcnt(12)
; #define SBAR() __builtin_amdgcn_sched_barrier(0)
; __device__ __forceinline__ void partialSM(f32x16& p0, f32x16& p1, float& m_reg, float& mn, float& alpha) {
;   constexpr float C = SCALE * 1.4426950408889634f;
;   float pmax = p0[0]; for (int r = 1; r < 16; ++r) pmax = fmaxf(pmax, p0[r]); for (int r = 0; r < 16; ++r) pmax = fmaxf(pmax, p1[r]);
;   { auto rr = __builtin_amdgcn_permlane32_swap(__float_as_uint(pmax), __float_as_uint(pmax), false, false);
;     pmax = fmaxf(__uint_as_float(rr[0]), __uint_as_float(rr[1])); }
;   if (__builtin_expect(__all(pmax - m_reg <= THR / SCALE), 1)) { mn = m_reg; alpha = 1.f; }
;   else { mn = fmaxf(m_reg, pmax); alpha = __builtin_amdgcn_exp2f((m_reg - mn) * C); m_reg = mn; }
;   float mnC = -mn * C;
;   for (int r = 0; r < 16; ++r) p0[r] = fmaf(p0[r], C, mnC); for (int r = 0; r < 16; ++r) p1[r] = fmaf(p1[r], C, mnC);
;   for (int r = 0; r < 16; ++r) p0[r] = __builtin_amdgcn_exp2f(p0[r]);
; }
; __device__ __forceinline__ void pv_d0(f32x16* o, int vb, bf16x8 pa0, bf16x8 pa1, bf16x8 pa2, bf16x8 pa3) {
;   VFrag fa, fb;
;   v_frag_read<0>(fa, vb);
;   asm volatile("s_waitcnt lgkmcnt(0)" ::: "memory"); SBAR();
;   v_frag_read<1>(fb, vb); SBAR();
;   pv_mma(o[0], fa, pa0, pa1, pa2, pa3); SBAR();
;   asm volatile("s_waitcnt lgkmcnt(0)" ::: "memory"); SBAR();
;   v_frag_read<2>(fa, vb); SBAR();
;   pv_mma(o[1], fb, pa0, pa1, pa2, pa3); SBAR();
;   asm volatile("s_waitcnt lgkmcnt(0)" ::: "memory"); SBAR();
;   v_frag_read<3>(fb, vb); SBAR();
;   pv_mma(o[2], fa, pa0, pa1, pa2, pa3); SBAR();
;   asm volatile("s_waitcnt lgkmcnt(0)" ::: "memory"); SBAR();
;   pv_mma(o[3], fb, pa0, pa1, pa2, pa3);
; }
	v_mfma_f32_32x32x16_bf16 v[18:33], v[70:73], v[232:235], v[18:33]
	v_max3_f32 v245, v245, v110, v111
	v_max3_f32 v245, v245, v112, v113
	v_max3_f32 v245, v245, v82, v83
	v_max3_f32 v245, v245, v84, v85
	v_max3_f32 v245, v245, v86, v87
	v_max3_f32 v245, v245, v88, v89
	v_max3_f32 v245, v245, v90, v91
	v_max3_f32 v245, v245, v92, v93
	s_waitcnt lgkmcnt(10)
	v_mfma_f32_32x32x16_bf16 v[18:33], v[74:77], v[236:239], v[18:33]
	v_max3_f32 v245, v245, v94, v95
	v_max3_f32 v245, v245, v96, v97
	v_mov_b32_e32 v246, v245
	s_nop 1
	v_permlane32_swap_b32_e32 v245, v246
	v_max_f32_e32 v246, v246, v246
	v_max_f32_e32 v245, v245, v245
	v_max_f32_e32 v245, v245, v246
	v_sub_f32_e32 v246, v245, v174
	s_waitcnt lgkmcnt(8)
	v_mfma_f32_32x32x16_bf16 v[18:33], v[78:81], v[240:243], v[18:33]
	v_cmp_ge_f32_e32 vcc, s63, v246
	v_max_f32_e32 v246, v174, v174
	v_max_f32_e32 v245, v246, v245
	v_sub_f32_e32 v246, v174, v245
	v_mul_f32_e32 v246, 0x3e38aa3b, v246
	v_exp_f32_e32 v246, v246
	s_cmp_eq_u64 vcc, exec
	s_cselect_b64 s[0:1], -1, 0
	v_cndmask_b32_e64 v132, v246, 1.0, s[0:1]
	ds_read_b64_tr_b16 v[228:229], v244 offset:0x400
	ds_read_b64_tr_b16 v[230:231], v244 offset:0xc00
	ds_read_b64_tr_b16 v[232:233], v244 offset:0x1400
	ds_read_b64_tr_b16 v[234:235], v244 offset:0x1c00
	ds_read_b64_tr_b16 v[236:237], v244 offset:0x2400
	ds_read_b64_tr_b16 v[238:239], v244 offset:0x2c00
	ds_read_b64_tr_b16 v[240:241], v244 offset:0x3400
	ds_read_b64_tr_b16 v[242:243], v244 offset:0x3c00
	v_cndmask_b32_e64 v133, v245, v174, s[0:1]
	v_mul_f32_e32 v148, 0xbe38aa3b, v133
	s_waitcnt lgkmcnt(14)
	v_mfma_f32_32x32x16_bf16 v[50:65], v[66:69], v[204:207], v[50:65]
	v_fmamk_f32 v98, v98, 0x3e38aa3b, v148
	v_fmamk_f32 v99, v99, 0x3e38aa3b, v148
	v_fmamk_f32 v100, v100, 0x3e38aa3b, v148
	v_fmamk_f32 v101, v101, 0x3e38aa3b, v148
	s_waitcnt lgkmcnt(12)
	v_mfma_f32_32x32x16_bf16 v[50:65], v[70:73], v[208:211], v[50:65]
	v_fmamk_f32 v102, v102, 0x3e38aa3b, v148
	v_fmamk_f32 v103, v103, 0x3e38aa3b, v148
	v_fmamk_f32 v104, v104, 0x3e38aa3b, v148
	v_fmamk_f32 v105, v105, 0x3e38aa3b, v148
	s_waitcnt lgkmcnt(10)
	v_mfma_f32_32x32x16_bf16 v[50:65], v[74:77], v[212:215], v[50:65]
	v_fmamk_f32 v106, v106, 0x3e38aa3b, v148
	v_fmamk_f32 v107, v107, 0x3e38aa3b, v148
	v_fmamk_f32 v108, v108, 0x3e38aa3b, v148
	v_fmamk_f32 v109, v109, 0x3e38aa3b, v148
	s_waitcnt lgkmcnt(8)
	v_mfma_f32_32x32x16_bf16 v[50:65], v[78:81], v[216:219], v[50:65]
	v_fmamk_f32 v110, v110, 0x3e38aa3b, v148
	v_fmamk_f32 v111, v111, 0x3e38aa3b, v148
	v_fmamk_f32 v112, v112, 0x3e38aa3b, v148
	v_fmamk_f32 v113, v113, 0x3e38aa3b, v148
	ds_read_b64_tr_b16 v[204:205], v244 offset:0x600
	ds_read_b64_tr_b16 v[206:207], v244 offset:0xe00
	ds_read_b64_tr_b16 v[208:209], v244 offset:0x1600
	ds_read_b64_tr_b16 v[210:211], v244 offset:0x1e00
	ds_read_b64_tr_b16 v[212:213], v244 offset:0x2600
	ds_read_b64_tr_b16 v[214:215], v244 offset:0x2e00
	ds_read_b64_tr_b16 v[216:217], v244 offset:0x3600
	ds_read_b64_tr_b16 v[218:219], v244 offset:0x3e00
	s_waitcnt lgkmcnt(14)
	v_mfma_f32_32x32x16_bf16 v[34:49], v[66:69], v[228:231], v[34:49]
	v_fmamk_f32 v82, v82, 0x3e38aa3b, v148
	v_fmamk_f32 v83, v83, 0x3e38aa3b, v148
	v_fmamk_f32 v84, v84, 0x3e38aa3b, v148
	v_fmamk_f32 v85, v85, 0x3e38aa3b, v148
	s_waitcnt lgkmcnt(12)
	v_mfma_f32_32x32x16_bf16 v[34:49], v[70:73], v[232:235], v[34:49]
	v_fmamk_f32 v86, v86, 0x3e38aa3b, v148
	v_fmamk_f32 v87, v87, 0x3e38aa3b, v148
	s_add_i32 s13, s36, 0xffff4000
	v_fmamk_f32 v149, v88, 0x3e38aa3b, v148
	s_waitcnt lgkmcnt(10)
	v_mfma_f32_32x32x16_bf16 v[34:49], v[74:77], v[236:239], v[34:49]
	v_fmamk_f32 v150, v89, 0x3e38aa3b, v148
	v_fmamk_f32 v151, v90, 0x3e38aa3b, v148
	v_fmamk_f32 v186, v91, 0x3e38aa3b, v148
	v_fmamk_f32 v187, v92, 0x3e38aa3b, v148
	s_waitcnt lgkmcnt(8)
	v_mfma_f32_32x32x16_bf16 v[34:49], v[78:81], v[240:243], v[34:49]
	v_fmamk_f32 v188, v93, 0x3e38aa3b, v148
	v_fmamk_f32 v189, v94, 0x3e38aa3b, v148
	v_exp_f32_e32 v192, v98
	v_exp_f32_e32 v193, v99
	v_exp_f32_e32 v194, v100
	v_exp_f32_e32 v195, v101
	s_waitcnt lgkmcnt(6)
	v_mfma_f32_32x32x16_bf16 v[2:17], v[66:69], v[204:207], v[2:17]
	v_exp_f32_e32 v196, v102
	v_exp_f32_e32 v197, v103
	v_exp_f32_e32 v198, v104
	v_exp_f32_e32 v199, v105
	s_waitcnt lgkmcnt(4)
	v_mfma_f32_32x32x16_bf16 v[2:17], v[70:73], v[208:211], v[2:17]
	v_exp_f32_e32 v200, v106
	v_exp_f32_e32 v201, v107
	v_exp_f32_e32 v202, v108
	v_exp_f32_e32 v203, v109
	v_exp_f32_e32 v204, v110
	v_exp_f32_e32 v205, v111
	s_waitcnt lgkmcnt(2)
	v_mfma_f32_32x32x16_bf16 v[2:17], v[74:77], v[212:215], v[2:17]
	v_exp_f32_e32 v206, v112
	v_exp_f32_e32 v207, v113
	v_fmamk_f32 v208, v95, 0x3e38aa3b, v148
	v_fmamk_f32 v209, v96, 0x3e38aa3b, v148
	v_fmac_f32_e32 v148, 0x3e38aa3b, v97
	s_waitcnt lgkmcnt(0)
	v_mfma_f32_32x32x16_bf16 v[2:17], v[78:81], v[216:219], v[2:17]
	v_add_u32_e32 v245, s101, v169
	v_add_u32_e32 v246, s101, v170
	v_add_u32_e32 v247, s101, v171
	v_add_u32_e32 v255, s101, v172
	v_cmp_gt_f32_e32 vcc, 1.0, v132
	s_cbranch_vccz .LBB0_774
	s_and_saveexec_b64 s[10:11], s[40:41]
	ds_write_b32 v162, v132 offset:128
	s_or_b64 exec, exec, s[10:11]
	s_waitcnt lgkmcnt(0)
	v_add_u32_e32 v67, s18, v140
	ds_read_b128 v[68:71], v67 offset:224
	ds_read_b128 v[72:75], v67 offset:192
	ds_read_b128 v[76:79], v67 offset:160
	ds_read_b128 v[134:137], v67 offset:128
	s_waitcnt lgkmcnt(0)
	v_pk_mul_f32 v[30:31], v[30:31], v[68:69]
	v_pk_mul_f32 v[26:27], v[26:27], v[72:73]
	v_pk_mul_f32 v[22:23], v[22:23], v[76:77]
	v_pk_mul_f32 v[32:33], v[32:33], v[70:71]
	v_pk_mul_f32 v[28:29], v[28:29], v[74:75]
	v_pk_mul_f32 v[24:25], v[24:25], v[78:79]
	v_pk_mul_f32 v[20:21], v[20:21], v[136:137]
	v_pk_mul_f32 v[18:19], v[18:19], v[134:135]
	v_pk_mul_f32 v[62:63], v[62:63], v[68:69]
	v_pk_mul_f32 v[58:59], v[58:59], v[72:73]
	v_pk_mul_f32 v[54:55], v[54:55], v[76:77]
	v_pk_mul_f32 v[64:65], v[64:65], v[70:71]
	v_pk_mul_f32 v[60:61], v[60:61], v[74:75]
	v_pk_mul_f32 v[56:57], v[56:57], v[78:79]
	v_pk_mul_f32 v[52:53], v[52:53], v[136:137]
	v_pk_mul_f32 v[50:51], v[50:51], v[134:135]
	v_pk_mul_f32 v[46:47], v[46:47], v[68:69]
	v_pk_mul_f32 v[42:43], v[42:43], v[72:73]
	v_pk_mul_f32 v[38:39], v[38:39], v[76:77]
	v_pk_mul_f32 v[48:49], v[48:49], v[70:71]
	v_pk_mul_f32 v[44:45], v[44:45], v[74:75]
	v_pk_mul_f32 v[40:41], v[40:41], v[78:79]
	v_pk_mul_f32 v[36:37], v[36:37], v[136:137]
	v_pk_mul_f32 v[34:35], v[34:35], v[134:135]
	v_pk_mul_f32 v[14:15], v[14:15], v[68:69]
	v_pk_mul_f32 v[10:11], v[10:11], v[72:73]
	v_pk_mul_f32 v[6:7], v[6:7], v[76:77]
	v_pk_mul_f32 v[16:17], v[16:17], v[70:71]
	v_pk_mul_f32 v[12:13], v[12:13], v[74:75]
	v_pk_mul_f32 v[8:9], v[8:9], v[78:79]
	v_pk_mul_f32 v[4:5], v[4:5], v[136:137]
	v_pk_mul_f32 v[2:3], v[2:3], v[134:135]
; #define SBAR() __builtin_amdgcn_sched_barrier(0)
; __device__ __forceinline__ void finishSM(f32x16& p0, f32x16& p1, float alpha, float& l_reg, bf16x8& pa0, bf16x8& pa1, bf16x8& pa2, bf16x8& pa3) {
;   for (int r = 0; r < 16; ++r) p1[r] = __builtin_amdgcn_exp2f(p1[r]);
;   float ps = 0; for (int r = 0; r < 16; ++r) ps += p0[r]; for (int r = 0; r < 16; ++r) ps += p1[r];
;   { auto rr = __builtin_amdgcn_permlane32_swap(__float_as_uint(ps), __float_as_uint(ps), false, false);
;     ps = __uint_as_float(rr[0]) + __uint_as_float(rr[1]); }
;   l_reg = l_reg * alpha + ps;
;     ...
;   PK4(p0, 0, pa0); PK4(p0, 8, pa1); PK4(p1, 0, pa2); PK4(p1, 8, pa3);
;     ...
; }
; __device__ __forceinline__ void kload(bf16x8 (&kf)[8], const char* Ks, int r32, int hi, int sb) {
; #pragma unroll
;   for (int d0 = 0; d0 < 4; ++d0) { const int cb = sb + (d0 * 16 + hi * 8) * 2;
;     kf[2 * d0] = *reinterpret_cast<const bf16x8*>(Ks + KSWZ(r32, cb)); kf[2 * d0 + 1] = *reinterpret_cast<const bf16x8*>(Ks + KSWZ(32 + r32, cb)); }
; }
; __device__ __forceinline__ void kmma(f32x16& p0, f32x16& p1, const bf16x8 (&kf)[8], const bf16x8* qr) {
;   asm volatile("s_waitcnt lgkmcnt(0)" ::: "memory"); SBAR();
;   p0 = f32x16{}; p1 = f32x16{};
; #pragma unroll
;   for (int d0 = 0; d0 < 4; ++d0) { p0 = __builtin_amdgcn_mfma_f32_32x32x16_bf16(kf[2 * d0], qr[d0], p0, 0, 0, 0); p1 = __builtin_amdgcn_mfma_f32_32x32x16_bf16(kf[2 * d0 + 1], qr[d0], p1, 0, 0, 0); }
; }
; __device__ __forceinline__ void qkt(f32x16& p0, f32x16& p1, const char* Ks, const bf16x8* qr, int r32, int hi, int sb) {
;   bf16x8 kf[8]; kload(kf, Ks, r32, hi, sb); SBAR(); kmma(p0, p1, kf, qr);
.LBB0_774:
	s_waitcnt vmcnt(4)
	s_barrier
	s_and_b32 s46, s13, 0xc000
	v_add_u32_e32 v244, s46, v164
	ds_read_b128 v[66:69], v245
	ds_read_b128 v[70:73], v245 offset:8192
	ds_read_b128 v[98:101], v246
	ds_read_b128 v[102:105], v246 offset:8192
	ds_read_b128 v[106:109], v247
	ds_read_b128 v[110:113], v247 offset:8192
	ds_read_b128 v[134:137], v255
	ds_read_b128 v[174:177], v255 offset:8192
	ds_read_b64_tr_b16 v[228:229], v244 offset:0
	ds_read_b64_tr_b16 v[230:231], v244 offset:0x800
	ds_read_b64_tr_b16 v[232:233], v244 offset:0x1000
	ds_read_b64_tr_b16 v[234:235], v244 offset:0x1800
	ds_read_b64_tr_b16 v[236:237], v244 offset:0x2000
	ds_read_b64_tr_b16 v[238:239], v244 offset:0x2800
	ds_read_b64_tr_b16 v[240:241], v244 offset:0x3000
	ds_read_b64_tr_b16 v[242:243], v244 offset:0x3800
	v_exp_f32_e32 v210, v82
	v_exp_f32_e32 v211, v83
	v_exp_f32_e32 v212, v84
	v_exp_f32_e32 v213, v85
	v_exp_f32_e32 v214, v86
	v_exp_f32_e32 v215, v87
	v_add_f32_e32 v216, 0, v192
	v_add_f32_e32 v216, v193, v216
	v_add_f32_e32 v216, v194, v216
	v_add_f32_e32 v216, v195, v216
	v_exp_f32_e32 v149, v149
	v_exp_f32_e32 v150, v150
	v_exp_f32_e32 v151, v151
	v_exp_f32_e32 v186, v186
	v_exp_f32_e32 v187, v187
	v_exp_f32_e32 v188, v188
	v_exp_f32_e32 v189, v189
	v_exp_f32_e32 v208, v208
	v_exp_f32_e32 v209, v209
	v_exp_f32_e32 v148, v148
	v_add_f32_e32 v255, v196, v216
	v_add_f32_e32 v255, v197, v255
	v_add_f32_e32 v255, v198, v255
	v_add_f32_e32 v255, v199, v255
	v_add_f32_e32 v255, v200, v255
	v_add_f32_e32 v255, v201, v255
	v_add_f32_e32 v255, v202, v255
	v_add_f32_e32 v255, v203, v255
	v_add_f32_e32 v255, v204, v255
	v_add_f32_e32 v255, v205, v255
	v_add_f32_e32 v255, v206, v255
	v_add_f32_e32 v255, v207, v255
	v_add_f32_e32 v255, v210, v255
	v_add_f32_e32 v255, v211, v255
	v_add_f32_e32 v255, v212, v255
	v_add_f32_e32 v255, v213, v255
	v_add_f32_e32 v255, v214, v255
	v_add_f32_e32 v255, v215, v255
	v_add_f32_e32 v255, v149, v255
	v_add_f32_e32 v255, v150, v255
	s_waitcnt lgkmcnt(15)
	v_mfma_f32_32x32x16_bf16 v[82:97], v[66:69], v[126:129], 0
	v_add_f32_e32 v255, v151, v255
	s_add_i32 s46, s12, 3
	s_cmpk_lt_u32 s12, 0x7d
	s_cselect_b64 s[42:43], -1, 0
	s_waitcnt lgkmcnt(14)
	v_mfma_f32_32x32x16_bf16 v[66:81], v[70:73], v[126:129], 0
	v_add_f32_e32 v255, v186, v255
	s_and_b64 s[44:45], s[42:43], exec
	s_cselect_b32 s44, 0, 0xffffff80
	s_add_i32 s58, s46, s44
	s_and_b64 s[42:43], s[42:43], exec
	s_waitcnt lgkmcnt(13)
	v_mfma_f32_32x32x16_bf16 v[82:97], v[98:101], v[122:125], v[82:97]
	v_add_f32_e32 v255, v187, v255
	s_cselect_b32 s43, s9, s30
	s_cselect_b32 s42, s8, s26
	s_lshl_b64 s[44:45], s[58:59], 17
	s_lshl_b64 s[42:43], s[42:43], 11
	s_waitcnt lgkmcnt(12)
	v_mfma_f32_32x32x16_bf16 v[66:81], v[102:105], v[122:125], v[66:81]
	v_add_f32_e32 v255, v188, v255
	s_add_u32 s44, s44, s42
	s_addc_u32 s45, s45, s43
	s_add_u32 s42, s20, s44
	s_waitcnt lgkmcnt(11)
	v_mfma_f32_32x32x16_bf16 v[82:97], v[106:109], v[118:121], v[82:97]
	v_add_f32_e32 v255, v189, v255
	s_addc_u32 s43, s21, s45
	s_add_u32 s44, s22, s44
	s_mul_i32 s47, s46, 0xab
	s_addc_u32 s45, s23, s45
	s_waitcnt lgkmcnt(10)
	v_mfma_f32_32x32x16_bf16 v[66:81], v[110:113], v[118:121], v[66:81]
	v_add_f32_e32 v255, v208, v255
	s_bfe_u32 s47, s47, 0x70009
	s_mul_i32 s47, s47, 3
	s_sub_i32 s46, s46, s47
	s_and_b32 s46, s46, 0xff
	s_waitcnt lgkmcnt(9)
	v_mfma_f32_32x32x16_bf16 v[82:97], v[134:137], v[114:117], v[82:97]
	v_add_f32_e32 v255, v209, v255
	s_lshl_b32 s46, s46, 14
	s_mov_b32 s101, s46
	v_add_f32_e32 v99, v148, v255
	s_add_i32 s46, s46, s27
	s_and_b32 s47, s36, 0xc000
	s_add_i32 s47, s47, s31
	s_cmpk_gt_u32 s12, 0x80
	s_cselect_b64 s[10:11], -1, 0
	s_and_b64 vcc, exec, s[10:11]
	s_cbranch_vccnz .LBB0_776
	v_lshl_add_u64 v[246:247], s[42:43], 0, v[146:147]
	s_mov_b32 m0, s46
	s_nop 0
	global_load_lds_dwordx4 v[246:247], off
	v_lshl_add_u64 v[246:247], s[44:45], 0, v[142:143]
	s_mov_b32 m0, s47
	s_nop 0
	global_load_lds_dwordx4 v[246:247], off
	v_lshl_add_u64 v[246:247], s[42:43], 0, v[144:145]
	s_add_i32 m0, s46, 0x2000
	s_nop 0
	global_load_lds_dwordx4 v[246:247], off
	v_lshl_add_u64 v[246:247], s[44:45], 0, v[154:155]
	s_add_i32 m0, s47, 0x2000
	s_nop 0
	global_load_lds_dwordx4 v[246:247], off
